# u-pass lane reduce-scatter (bank-masked DPP) instead of 16 full reductions; P8 init loads issued together; P7 touches next tile's query rows
# speedup vs baseline: 1.0236x; 1.0000x over previous
; __device__ __forceinline__ void row_to_fp8(const float* src, unsigned char* tab, int e, float* sc, int lane) {
;     f32x4 v[2][4]; float mx = 0.f;
; #pragma unroll
;     for (int c = 0; c < 2; ++c)
; #pragma unroll
;         for (int k = 0; k < 4; ++k) { v[c][k] = __builtin_nontemporal_load((const f32x4*)(src + c * 1024 + lane * 16 + k * 4));
;             mx = fmaxf(mx, fmaxf(fmaxf(fabsf(v[c][k].x), fabsf(v[c][k].y)), fmaxf(fabsf(v[c][k].z), fabsf(v[c][k].w)))); }
; #pragma unroll
;     for (int o = 1; o < 64; o <<= 1) mx = fmaxf(mx, __shfl_xor(mx, o));
;     const float scale = mx > 0.f ? 224.f / mx : 1.f;
; #pragma unroll
;     for (int c = 0; c < 2; ++c) { u32x4 w;
; #pragma unroll
;         for (int k = 0; k < 4; ++k) { const f32x4 x = v[c][k] * scale; int pk = 0; pk = __builtin_amdgcn_cvt_pk_fp8_f32(x.x, x.y, pk, false); pk = __builtin_amdgcn_cvt_pk_fp8_f32(x.z, x.w, pk, true); w[k] = (unsigned)pk; }
;         *(u32x4*)(tab + (size_t)(c * 8 + (lane >> 3)) * (16384 * 128) + (size_t)e * 128 + (lane & 7) * 16) = w; }
;     if (lane == 0) *sc = mx > 0.f ? mx * (1.f / 224.f) : 1.f;
; }
.Lcv_tj:
	v_lshlrev_b32_e32 v148, 2, v148
	v_add_co_u32_e32 v142, vcc, 0x1000000, v140
	s_nop 1
	v_addc_co_u32_e32 v143, vcc, 0, v141, vcc
	v_max3_f32 v144, |v150|, |v151|, |v152|
	v_max3_f32 v145, |v153|, |v154|, |v155|
	v_max3_f32 v146, |v156|, |v157|, |v158|
	v_max3_f32 v147, |v159|, |v160|, |v161|
	v_max3_f32 v144, |v162|, |v163|, v144
	v_max3_f32 v145, |v164|, |v165|, v145
	v_max3_f32 v146, |v166|, |v167|, v146
	v_max3_f32 v147, |v168|, |v169|, v147
	v_max3_f32 v144, |v170|, |v171|, v144
	v_max3_f32 v145, |v172|, |v173|, v145
	v_max3_f32 v146, |v174|, |v175|, v146
	v_max3_f32 v147, |v176|, |v177|, v147
	v_max3_f32 v144, |v178|, |v179|, v144
	v_max3_f32 v145, |v180|, |v181|, v145
	v_max3_f32 v144, v144, v145, v146
	s_nop 0
	v_max_f32_e32 v144, v144, v147
	s_nop 1
	v_max_f32_dpp v144, v144, v144 quad_perm:[1,0,3,2] row_mask:0xf bank_mask:0xf bound_ctrl:1
	s_nop 1
	v_max_f32_dpp v144, v144, v144 quad_perm:[2,3,0,1] row_mask:0xf bank_mask:0xf bound_ctrl:1
	s_nop 1
	v_max_f32_dpp v144, v144, v144 row_half_mirror row_mask:0xf bank_mask:0xf bound_ctrl:1
	s_nop 1
	v_max_f32_dpp v144, v144, v144 row_mirror row_mask:0xf bank_mask:0xf bound_ctrl:1
	s_nop 1
	v_readlane_b32 s98, v144, 0
	v_readlane_b32 s99, v144, 16
	v_readlane_b32 vcc_lo, v144, 32
	v_readlane_b32 vcc_hi, v144, 48
	s_max_u32 s98, s98, s99
	s_max_u32 vcc_lo, vcc_lo, vcc_hi
	s_max_u32 s98, s98, vcc_lo
	v_mov_b32_e32 v149, s98
	v_div_scale_f32 v224, vcc, v149, v149, s70
	v_rcp_f32_e32 v225, v224
	v_div_scale_f32 v226, vcc, s70, v149, s70
	v_cmp_lt_f32_e64 s[98:99], 0, v149
	v_fma_f32 v227, -v224, v225, 1.0
	v_fmac_f32_e32 v225, v227, v225
	v_mul_f32_e32 v227, v226, v225
	v_fma_f32 v228, -v224, v227, v226
	v_fmac_f32_e32 v227, v228, v225
	v_fma_f32 v224, -v224, v227, v226
	v_div_fmas_f32 v224, v224, v225, v227
	v_div_fixup_f32 v224, v224, v149, s70
	v_mul_f32_e32 v229, 0x3b924925, v149
	v_cndmask_b32_e64 v230, 1.0, v224, s[98:99]
	v_cndmask_b32_e64 v229, 1.0, v229, s[98:99]
	v_pk_mul_f32 v[150:151], v[150:151], v[230:231] op_sel_hi:[1,0]
	v_pk_mul_f32 v[152:153], v[152:153], v[230:231] op_sel_hi:[1,0]
	v_pk_mul_f32 v[154:155], v[154:155], v[230:231] op_sel_hi:[1,0]
	v_pk_mul_f32 v[156:157], v[156:157], v[230:231] op_sel_hi:[1,0]
	v_pk_mul_f32 v[158:159], v[158:159], v[230:231] op_sel_hi:[1,0]
	v_pk_mul_f32 v[160:161], v[160:161], v[230:231] op_sel_hi:[1,0]
	v_pk_mul_f32 v[162:163], v[162:163], v[230:231] op_sel_hi:[1,0]
	v_pk_mul_f32 v[164:165], v[164:165], v[230:231] op_sel_hi:[1,0]
	v_pk_mul_f32 v[166:167], v[166:167], v[230:231] op_sel_hi:[1,0]
	v_pk_mul_f32 v[168:169], v[168:169], v[230:231] op_sel_hi:[1,0]
	v_pk_mul_f32 v[170:171], v[170:171], v[230:231] op_sel_hi:[1,0]
	v_pk_mul_f32 v[172:173], v[172:173], v[230:231] op_sel_hi:[1,0]
	v_pk_mul_f32 v[174:175], v[174:175], v[230:231] op_sel_hi:[1,0]
	v_pk_mul_f32 v[176:177], v[176:177], v[230:231] op_sel_hi:[1,0]
	v_pk_mul_f32 v[178:179], v[178:179], v[230:231] op_sel_hi:[1,0]
	v_pk_mul_f32 v[180:181], v[180:181], v[230:231] op_sel_hi:[1,0]
	v_cvt_pk_fp8_f32 v216, v150, v151
	v_cvt_pk_fp8_f32 v217, v154, v155
	v_cvt_pk_fp8_f32 v218, v158, v159
	v_cvt_pk_fp8_f32 v219, v162, v163
	v_cvt_pk_fp8_f32 v220, v166, v167
	v_cvt_pk_fp8_f32 v221, v170, v171
	v_cvt_pk_fp8_f32 v222, v174, v175
	v_cvt_pk_fp8_f32 v223, v178, v179
	v_cvt_pk_fp8_f32 v216, v152, v153 op_sel:[0,0,1]
	v_cvt_pk_fp8_f32 v217, v156, v157 op_sel:[0,0,1]
	v_cvt_pk_fp8_f32 v218, v160, v161 op_sel:[0,0,1]
	v_cvt_pk_fp8_f32 v219, v164, v165 op_sel:[0,0,1]
	v_cvt_pk_fp8_f32 v220, v168, v169 op_sel:[0,0,1]
	v_cvt_pk_fp8_f32 v221, v172, v173 op_sel:[0,0,1]
	v_cvt_pk_fp8_f32 v222, v176, v177 op_sel:[0,0,1]
	v_cvt_pk_fp8_f32 v223, v180, v181 op_sel:[0,0,1]
	s_nop 0
	global_store_dwordx4 v[140:141], v[216:219], off
	global_store_dwordx4 v[142:143], v[220:223], off
	global_store_dword v148, v229, s[100:101]
	v_max3_f32 v144, |v182|, |v183|, |v184|
	v_max3_f32 v145, |v185|, |v186|, |v187|
	v_max3_f32 v146, |v188|, |v189|, |v190|
	v_max3_f32 v147, |v191|, |v192|, |v193|
	v_max3_f32 v144, |v194|, |v195|, v144
	v_max3_f32 v145, |v196|, |v197|, v145
	v_max3_f32 v146, |v198|, |v199|, v146
	v_max3_f32 v147, |v200|, |v201|, v147
	v_max3_f32 v144, |v202|, |v203|, v144
	v_max3_f32 v145, |v204|, |v205|, v145
	v_max3_f32 v146, |v206|, |v207|, v146
	v_max3_f32 v147, |v208|, |v209|, v147
	v_max3_f32 v144, |v210|, |v211|, v144
	v_max3_f32 v145, |v212|, |v213|, v145
	v_max3_f32 v144, v144, v145, v146
	s_nop 0
	v_max_f32_e32 v144, v144, v147
	s_nop 1
	v_max_f32_dpp v144, v144, v144 quad_perm:[1,0,3,2] row_mask:0xf bank_mask:0xf bound_ctrl:1
	s_nop 1
	v_max_f32_dpp v144, v144, v144 quad_perm:[2,3,0,1] row_mask:0xf bank_mask:0xf bound_ctrl:1
	s_nop 1
	v_max_f32_dpp v144, v144, v144 row_half_mirror row_mask:0xf bank_mask:0xf bound_ctrl:1
	s_nop 1
	v_max_f32_dpp v144, v144, v144 row_mirror row_mask:0xf bank_mask:0xf bound_ctrl:1
	s_nop 1
	v_readlane_b32 s98, v144, 0
	v_readlane_b32 s99, v144, 16
	v_readlane_b32 vcc_lo, v144, 32
	v_readlane_b32 vcc_hi, v144, 48
	s_max_u32 s98, s98, s99
	s_max_u32 vcc_lo, vcc_lo, vcc_hi
	s_max_u32 s98, s98, vcc_lo
	v_mov_b32_e32 v149, s98
	v_div_scale_f32 v224, vcc, v149, v149, s70
	v_rcp_f32_e32 v225, v224
	v_div_scale_f32 v226, vcc, s70, v149, s70
	v_cmp_lt_f32_e64 s[98:99], 0, v149
	v_fma_f32 v227, -v224, v225, 1.0
	v_fmac_f32_e32 v225, v227, v225
	v_mul_f32_e32 v227, v226, v225
	v_fma_f32 v228, -v224, v227, v226
	v_fmac_f32_e32 v227, v228, v225
	v_fma_f32 v224, -v224, v227, v226
	v_div_fmas_f32 v224, v224, v225, v227
	v_div_fixup_f32 v224, v224, v149, s70
	v_mul_f32_e32 v229, 0x3b924925, v149
	v_cndmask_b32_e64 v230, 1.0, v224, s[98:99]
	v_cndmask_b32_e64 v229, 1.0, v229, s[98:99]
; __device__ __forceinline__ void row_to_fp8(const float* src, unsigned char* tab, int e, float* sc, int lane) {
;     ...
;     for (int c = 0; c < 2; ++c) { u32x4 w;
; #pragma unroll
;         for (int k = 0; k < 4; ++k) { const f32x4 x = v[c][k] * scale; int pk = 0; pk = __builtin_amdgcn_cvt_pk_fp8_f32(x.x, x.y, pk, false); pk = __builtin_amdgcn_cvt_pk_fp8_f32(x.z, x.w, pk, true); w[k] = (unsigned)pk; }
;         *(u32x4*)(tab + (size_t)(c * 8 + (lane >> 3)) * (16384 * 128) + (size_t)e * 128 + (lane & 7) * 16) = w; }
;     if (lane == 0) *sc = mx > 0.f ? mx * (1.f / 224.f) : 1.f;
; __global__ void __launch_bounds__(NTHR, 2) fwd_megakernel(Args a) {
;     ...
;             const int h = tile & 7, t0 = (tile >> 3) * 128;
;             {
;                 const int p = wave >> 2, r0 = (wave & 3) * 32;
;                 f32x16 acc[4];
; #pragma unroll
;                 for (int nb = 0; nb < 4; ++nb)
; #pragma unroll
;                     for (int i = 0; i < 16; ++i) acc[nb][i] = 0.f;
;                 const bf16_t* qa = QP + (size_t)(t0 + r0 + l31) * 2048 + h * 256 + p * 128 + hi * 8;
;                 const bf16_t* kb = KEYS + (size_t)((h * 2 + p) * 128 + l31) * 128 + hi * 8;
; #pragma unroll
;                 for (int ks = 0; ks < 8; ++ks) {
;                     const bf16x8 af = *(const bf16x8*)(qa + ks * 16);
; #pragma unroll
;                     for (int nb = 0; nb < 4; ++nb) { const bf16x8 bf = *(const bf16x8*)(kb + nb * 32 * 128 + ks * 16); acc[nb] = __builtin_amdgcn_mfma_f32_32x32x16_bf16(af, bf, acc[nb], 0, 0, 0); }
;                 }
	v_pk_mul_f32 v[182:183], v[182:183], v[230:231] op_sel_hi:[1,0]
	v_pk_mul_f32 v[184:185], v[184:185], v[230:231] op_sel_hi:[1,0]
	v_pk_mul_f32 v[186:187], v[186:187], v[230:231] op_sel_hi:[1,0]
	v_pk_mul_f32 v[188:189], v[188:189], v[230:231] op_sel_hi:[1,0]
	v_pk_mul_f32 v[190:191], v[190:191], v[230:231] op_sel_hi:[1,0]
	v_pk_mul_f32 v[192:193], v[192:193], v[230:231] op_sel_hi:[1,0]
	v_pk_mul_f32 v[194:195], v[194:195], v[230:231] op_sel_hi:[1,0]
	v_pk_mul_f32 v[196:197], v[196:197], v[230:231] op_sel_hi:[1,0]
	v_pk_mul_f32 v[198:199], v[198:199], v[230:231] op_sel_hi:[1,0]
	v_pk_mul_f32 v[200:201], v[200:201], v[230:231] op_sel_hi:[1,0]
	v_pk_mul_f32 v[202:203], v[202:203], v[230:231] op_sel_hi:[1,0]
	v_pk_mul_f32 v[204:205], v[204:205], v[230:231] op_sel_hi:[1,0]
	v_pk_mul_f32 v[206:207], v[206:207], v[230:231] op_sel_hi:[1,0]
	v_pk_mul_f32 v[208:209], v[208:209], v[230:231] op_sel_hi:[1,0]
	v_pk_mul_f32 v[210:211], v[210:211], v[230:231] op_sel_hi:[1,0]
	v_pk_mul_f32 v[212:213], v[212:213], v[230:231] op_sel_hi:[1,0]
	v_cvt_pk_fp8_f32 v216, v182, v183
	v_cvt_pk_fp8_f32 v217, v186, v187
	v_cvt_pk_fp8_f32 v218, v190, v191
	v_cvt_pk_fp8_f32 v219, v194, v195
	v_cvt_pk_fp8_f32 v220, v198, v199
	v_cvt_pk_fp8_f32 v221, v202, v203
	v_cvt_pk_fp8_f32 v222, v206, v207
	v_cvt_pk_fp8_f32 v223, v210, v211
	v_cvt_pk_fp8_f32 v216, v184, v185 op_sel:[0,0,1]
	v_cvt_pk_fp8_f32 v217, v188, v189 op_sel:[0,0,1]
	v_cvt_pk_fp8_f32 v218, v192, v193 op_sel:[0,0,1]
	v_cvt_pk_fp8_f32 v219, v196, v197 op_sel:[0,0,1]
	v_cvt_pk_fp8_f32 v220, v200, v201 op_sel:[0,0,1]
	v_cvt_pk_fp8_f32 v221, v204, v205 op_sel:[0,0,1]
	v_cvt_pk_fp8_f32 v222, v208, v209 op_sel:[0,0,1]
	v_cvt_pk_fp8_f32 v223, v212, v213 op_sel:[0,0,1]
	s_nop 0
	global_store_dwordx4 v[140:141], v[216:219], off offset:128
	global_store_dwordx4 v[142:143], v[220:223], off offset:128
	global_store_dword v148, v229, s[100:101] offset:4
	s_lshl_b32 s0, s73, 4
	s_and_b32 s75, s0, 0xffffff80
	v_or_b32_e32 v0, s75, v77
	v_ashrrev_i32_e32 v1, 31, v0
	v_readlane_b32 s0, v235, 49
	s_and_b32 s74, s73, 7
	v_lshlrev_b64 v[0:1], 12, v[0:1]
	v_readlane_b32 s1, v235, 50
	s_lshl_b32 s44, s74, 9
	s_nop 0
	v_lshl_add_u64 v[0:1], s[0:1], 0, v[0:1]
	v_lshl_add_u64 v[0:1], v[0:1], 0, s[44:45]
	v_lshl_add_u64 v[0:1], s[34:35], 1, v[0:1]
	v_lshl_add_u64 v[130:131], v[0:1], 0, v[64:65]
	v_lshl_add_u32 v0, s74, 8, v78
	v_ashrrev_i32_e32 v1, 31, v0
	v_lshlrev_b64 v[0:1], 8, v[0:1]
	v_lshl_add_u64 v[132:133], v[66:67], 0, v[0:1]
	global_load_dwordx4 v[16:19], v[130:131], off
	global_load_dwordx4 v[0:3], v[132:133], off
	v_add_co_u32_e32 v134, vcc, s66, v132
	s_mov_b32 s44, 64
	s_nop 0
	v_addc_co_u32_e32 v135, vcc, 0, v133, vcc
	v_add_co_u32_e32 v136, vcc, s67, v132
	global_load_dwordx4 v[4:7], v[134:135], off
	s_nop 0
	v_addc_co_u32_e32 v137, vcc, 0, v133, vcc
	global_load_dwordx4 v[8:11], v[136:137], off
	v_add_co_u32_e32 v138, vcc, s68, v132
	s_waitcnt vmcnt(2)
	v_mfma_f32_32x32x16_bf16 v[32:47], v[16:19], v[0:3], 0
	v_addc_co_u32_e32 v139, vcc, 0, v133, vcc
	global_load_dwordx4 v[20:23], v[138:139], off
	global_load_dwordx4 v[98:101], v[130:131], off offset:32
	global_load_dwordx4 v[102:105], v[132:133], off offset:32
	global_load_dwordx4 v[106:109], v[134:135], off offset:32
	global_load_dwordx4 v[110:113], v[136:137], off offset:32
	global_load_dwordx4 v[114:117], v[138:139], off offset:32
	global_load_dwordx4 v[118:121], v[130:131], off offset:64
	global_load_dwordx4 v[122:125], v[132:133], off offset:64
	s_waitcnt vmcnt(9)
	v_mfma_f32_32x32x16_bf16 v[48:63], v[16:19], v[4:7], 0
	s_waitcnt vmcnt(8)
	v_mfma_f32_32x32x16_bf16 v[0:15], v[16:19], v[8:11], 0
	s_waitcnt vmcnt(7)
	v_mfma_f32_32x32x16_bf16 v[16:31], v[16:19], v[20:23], 0
	s_waitcnt vmcnt(5)
	v_mfma_f32_32x32x16_bf16 v[32:47], v[98:101], v[102:105], v[32:47]
	global_load_dwordx4 v[102:105], v[134:135], off offset:64
	s_waitcnt vmcnt(5)
	v_mfma_f32_32x32x16_bf16 v[48:63], v[98:101], v[106:109], v[48:63]
	global_load_dwordx4 v[106:109], v[136:137], off offset:64
	s_waitcnt vmcnt(5)
	v_mfma_f32_32x32x16_bf16 v[0:15], v[98:101], v[110:113], v[0:15]
	global_load_dwordx4 v[110:113], v[138:139], off offset:64
	global_load_dwordx4 v[126:129], v[130:131], off offset:96
	s_waitcnt vmcnt(6)
	v_mfma_f32_32x32x16_bf16 v[16:31], v[98:101], v[114:117], v[16:31]
	global_load_dwordx4 v[98:101], v[132:133], off offset:96
	global_load_dwordx4 v[114:117], v[134:135], off offset:96
	s_waitcnt vmcnt(6)
	v_mfma_f32_32x32x16_bf16 v[32:47], v[118:121], v[122:125], v[32:47]
	s_waitcnt vmcnt(5)
	v_mfma_f32_32x32x16_bf16 v[48:63], v[118:121], v[102:105], v[48:63]
	global_load_dwordx4 v[102:105], v[136:137], off offset:96
	s_waitcnt vmcnt(5)
	v_mfma_f32_32x32x16_bf16 v[0:15], v[118:121], v[106:109], v[0:15]
	global_load_dwordx4 v[106:109], v[138:139], off offset:96
	global_load_dwordx4 v[122:125], v[130:131], off offset:128
	s_waitcnt vmcnt(6)
	v_mfma_f32_32x32x16_bf16 v[16:31], v[118:121], v[110:113], v[16:31]
	global_load_dwordx4 v[110:113], v[132:133], off offset:128
	s_waitcnt vmcnt(5)
	v_mfma_f32_32x32x16_bf16 v[32:47], v[126:129], v[98:101], v[32:47]
	global_load_dwordx4 v[98:101], v[134:135], off offset:128
	s_waitcnt vmcnt(5)
	v_mfma_f32_32x32x16_bf16 v[48:63], v[126:129], v[114:117], v[48:63]
	global_load_dwordx4 v[114:117], v[136:137], off offset:128
	s_waitcnt vmcnt(5)
; __device__ __forceinline__ int crow(int r, int hi) { return (r & 3) + 8 * (r >> 2) + 4 * hi; }
; __global__ void __launch_bounds__(NTHR, 2) fwd_megakernel(Args a) {
;     ...
;                 for (int ks = 0; ks < 8; ++ks) {
;                     const bf16x8 af = *(const bf16x8*)(qa + ks * 16);
; #pragma unroll
;                     for (int nb = 0; nb < 4; ++nb) { const bf16x8 bf = *(const bf16x8*)(kb + nb * 32 * 128 + ks * 16); acc[nb] = __builtin_amdgcn_mfma_f32_32x32x16_bf16(af, bf, acc[nb], 0, 0, 0); }
;                 }
; #pragma unroll
;                 for (int nb = 0; nb < 4; ++nb)
; #pragma unroll
;                     for (int i = 0; i < 16; ++i) SC[(p * 128 + r0 + crow(i, hi)) * 129 + nb * 32 + l31] = acc[nb][i];
;             }
;             __syncthreads();
;             {
;                 const int row = tid & 255, hf = tid >> 8;
;                 unsigned v[16];
; #pragma unroll
;                 for (int j = 0; j < 16; ++j) v[j] = 0u;
	v_mfma_f32_32x32x16_bf16 v[0:15], v[126:129], v[102:105], v[0:15]
	global_load_dwordx4 v[102:105], v[138:139], off offset:128
	global_load_dwordx4 v[118:121], v[130:131], off offset:160
	s_waitcnt vmcnt(4)
	v_mfma_f32_32x32x16_bf16 v[32:47], v[122:125], v[110:113], v[32:47]
	global_load_dwordx4 v[110:113], v[134:135], off offset:160
	s_waitcnt vmcnt(4)
	v_mfma_f32_32x32x16_bf16 v[48:63], v[122:125], v[98:101], v[48:63]
	global_load_dwordx4 v[98:101], v[136:137], off offset:160
	v_mfma_f32_32x32x16_bf16 v[16:31], v[126:129], v[106:109], v[16:31]
	global_load_dwordx4 v[106:109], v[132:133], off offset:160
	s_waitcnt vmcnt(5)
	v_mfma_f32_32x32x16_bf16 v[0:15], v[122:125], v[114:117], v[0:15]
	global_load_dwordx4 v[114:117], v[138:139], off offset:160
	s_waitcnt vmcnt(2)
	v_mfma_f32_32x32x16_bf16 v[0:15], v[118:121], v[98:101], v[0:15]
	global_load_dwordx4 v[98:101], v[130:131], off offset:192
	v_mfma_f32_32x32x16_bf16 v[16:31], v[122:125], v[102:105], v[16:31]
	s_waitcnt vmcnt(2)
	v_mfma_f32_32x32x16_bf16 v[32:47], v[118:121], v[106:109], v[32:47]
	v_mfma_f32_32x32x16_bf16 v[48:63], v[118:121], v[110:113], v[48:63]
	global_load_dwordx4 v[102:105], v[132:133], off offset:192
	global_load_dwordx4 v[106:109], v[130:131], off offset:224
	global_load_dwordx4 v[110:113], v[132:133], off offset:224
	s_waitcnt vmcnt(4)
	v_mfma_f32_32x32x16_bf16 v[16:31], v[118:121], v[114:117], v[16:31]
	s_waitcnt vmcnt(2)
	v_mfma_f32_32x32x16_bf16 v[32:47], v[98:101], v[102:105], v[32:47]
	global_load_dwordx4 v[102:105], v[134:135], off offset:192
	global_load_dwordx4 v[114:117], v[134:135], off offset:224
	s_waitcnt vmcnt(1)
	v_mfma_f32_32x32x16_bf16 v[48:63], v[98:101], v[102:105], v[48:63]
	global_load_dwordx4 v[102:105], v[136:137], off offset:192
	global_load_dwordx4 v[118:121], v[136:137], off offset:224
	s_waitcnt vmcnt(1)
	v_mfma_f32_32x32x16_bf16 v[0:15], v[98:101], v[102:105], v[0:15]
	global_load_dwordx4 v[102:105], v[138:139], off offset:192
	v_mfma_f32_32x32x16_bf16 v[32:47], v[106:109], v[110:113], v[32:47]
	global_load_dwordx4 v[110:113], v[138:139], off offset:224
	s_waitcnt vmcnt(1)
	v_mfma_f32_32x32x16_bf16 v[16:31], v[98:101], v[102:105], v[16:31]
	v_mfma_f32_32x32x16_bf16 v[48:63], v[106:109], v[114:117], v[48:63]
	s_nop 11
	ds_write2_b32 v84, v32, v48 offset1:32
	ds_write2_b32 v84, v33, v49 offset0:129 offset1:161
	v_mfma_f32_32x32x16_bf16 v[0:15], v[106:109], v[118:121], v[0:15]
	ds_write2_b32 v89, v34, v50 offset0:2 offset1:34
	ds_write2_b32 v89, v35, v51 offset0:131 offset1:163
	ds_write2_b32 v90, v36, v52 offset0:8 offset1:40
	ds_write2_b32 v90, v37, v53 offset0:137 offset1:169
	ds_write2_b32 v91, v38, v54 offset0:10 offset1:42
	ds_write2_b32 v91, v39, v55 offset0:139 offset1:171
	ds_write2_b32 v92, v40, v56 offset0:16 offset1:48
	ds_write2_b32 v92, v41, v57 offset0:145 offset1:177
	ds_write2_b32 v93, v42, v58 offset0:18 offset1:50
	ds_write2_b32 v93, v43, v59 offset0:147 offset1:179
	ds_write2_b32 v94, v44, v60 offset0:24 offset1:56
	ds_write2_b32 v94, v45, v61 offset0:153 offset1:185
	ds_write2_b32 v95, v46, v62 offset0:26 offset1:58
	ds_write2_b32 v95, v47, v63 offset0:155 offset1:187
	s_waitcnt vmcnt(0)
	v_mfma_f32_32x32x16_bf16 v[16:31], v[106:109], v[110:113], v[16:31]
	s_nop 11
	ds_write2_b32 v84, v0, v16 offset0:64 offset1:96
	ds_write2_b32 v84, v1, v17 offset0:193 offset1:225
	ds_write2_b32 v89, v2, v18 offset0:66 offset1:98
	ds_write2_b32 v89, v3, v19 offset0:195 offset1:227
	ds_write2_b32 v90, v4, v20 offset0:72 offset1:104
	ds_write2_b32 v90, v5, v21 offset0:201 offset1:233
	ds_write2_b32 v91, v6, v22 offset0:74 offset1:106
	ds_write2_b32 v91, v7, v23 offset0:203 offset1:235
	ds_write2_b32 v92, v8, v24 offset0:80 offset1:112
	ds_write2_b32 v92, v9, v25 offset0:209 offset1:241
	ds_write2_b32 v93, v10, v26 offset0:82 offset1:114
	ds_write2_b32 v93, v11, v27 offset0:211 offset1:243
	ds_write2_b32 v94, v12, v28 offset0:88 offset1:120
	ds_write2_b32 v94, v13, v29 offset0:217 offset1:249
	ds_write2_b32 v95, v14, v30 offset0:90 offset1:122
	ds_write2_b32 v95, v15, v31 offset0:219 offset1:251
	v_mov_b32_e32 v24, v79
	v_mov_b32_e32 v0, 0
	v_mov_b32_e32 v1, 0
	v_mov_b32_e32 v2, 0
	v_mov_b32_e32 v3, 0
	v_mov_b32_e32 v4, 0
	v_mov_b32_e32 v5, 0
	v_mov_b32_e32 v6, 0
	v_mov_b32_e32 v7, 0
	v_mov_b32_e32 v8, 0
	v_mov_b32_e32 v9, 0
	v_mov_b32_e32 v10, 0
	v_mov_b32_e32 v11, 0
	v_mov_b32_e32 v12, 0
	v_mov_b32_e32 v13, 0
	v_mov_b32_e32 v14, 0
	v_mov_b32_e32 v15, 0
	s_waitcnt lgkmcnt(0)
	s_barrier
	v_readlane_b32 s98, v235, 1
	s_nop 0
	s_add_i32 s98, s73, s98
	s_cmpk_gt_i32 s98, 0x7ff
	s_cbranch_scc1 .Lcv_nopf_b
	s_lshr_b32 s99, s98, 3
	s_lshl_b32 s99, s99, 19
	s_and_b32 s100, s98, 7
	s_lshl_b32 s100, s100, 9
	s_add_i32 s99, s99, s100
	s_add_u32 s100, s50, 0x24000000
	s_addc_u32 s101, s51, 0
	s_add_u32 s100, s100, s99
	s_addc_u32 s101, s101, 0
	v_lshrrev_b32_e32 v140, 2, v214
	v_and_b32_e32 v141, 3, v214
	v_lshlrev_b32_e32 v140, 12, v140
	v_lshl_or_b32 v140, v141, 7, v140
	global_load_dword v148, v140, s[100:101]
	s_lshl_b32 s98, s98, 4
	s_add_i32 s99, s59, 4
	s_lshl_b32 s99, s99, 1
	s_add_i32 s98, s98, s99
	s_and_b32 s99, s98, 0x3fff
	s_lshl_b32 s100, s99, 13
	s_mov_b32 s101, 0
	s_cmpk_gt_i32 s98, 0x3fff
	s_cbranch_scc1 .Lcv_pfv_b
	v_lshl_add_u64 v[140:141], v[72:73], 0, s[100:101]
	s_branch .Lcv_pfj_b

; __global__ void __launch_bounds__(NTHR, 2) fwd_megakernel(Args a) {
;     ...
;         for (int k0 = 0; k0 < KT; k0 += 16) {
;             const int kn = (KT - k0) < 16 ? (KT - k0) : 16;
;             for (int k = 0; k < kn; ++k) { const size_t t = (size_t)gw + (size_t)(k0 + k) * NGW;
;                 EL[k * 128 + lane] = EXPI[t * 128 + lane]; EL[k * 128 + 64 + lane] = EXPI[t * 128 + 64 + lane]; HW[k * 128 + lane] = 0.f; HW[k * 128 + 64 + lane] = 0.f; }
.LBB0_879:
	s_sub_i32 s97, s66, s76
	s_cmp_gt_i32 s97, 0
	v_med3_i32 v0, s95, 1, 16
	s_cselect_b64 s[0:1], -1, 0
	v_readfirstlane_b32 s33, v0
	s_and_b64 vcc, exec, s[0:1]
	s_cbranch_vccz .LBB0_891
	s_mul_i32 s98, s76, s84
	s_add_i32 s98, s98, s38
	s_lshl_b32 s98, s98, 9
	s_mov_b32 s99, 0
	s_lshl_b32 s100, s84, 9
	v_lshl_add_u64 v[32:33], v[80:81], 0, s[98:99]
	global_load_dword v0, v[32:33], off
	global_load_dword v1, v[32:33], off offset:256
	s_add_u32 s98, s98, s100
	s_cmp_le_u32 s33, 1
	s_cbranch_scc1 .Lini_ld_done
	v_lshl_add_u64 v[34:35], v[80:81], 0, s[98:99]
	global_load_dword v2, v[34:35], off
	global_load_dword v3, v[34:35], off offset:256
	s_add_u32 s98, s98, s100
	s_cmp_le_u32 s33, 2
	s_cbranch_scc1 .Lini_ld_done
	v_lshl_add_u64 v[32:33], v[80:81], 0, s[98:99]
	global_load_dword v4, v[32:33], off
	global_load_dword v5, v[32:33], off offset:256
	s_add_u32 s98, s98, s100
	s_cmp_le_u32 s33, 3
	s_cbranch_scc1 .Lini_ld_done
	v_lshl_add_u64 v[34:35], v[80:81], 0, s[98:99]
	global_load_dword v6, v[34:35], off
	global_load_dword v7, v[34:35], off offset:256
	s_add_u32 s98, s98, s100
	s_cmp_le_u32 s33, 4
	s_cbranch_scc1 .Lini_ld_done
	v_lshl_add_u64 v[32:33], v[80:81], 0, s[98:99]
	global_load_dword v8, v[32:33], off
	global_load_dword v9, v[32:33], off offset:256
	s_add_u32 s98, s98, s100
	s_cmp_le_u32 s33, 5
	s_cbranch_scc1 .Lini_ld_done
	v_lshl_add_u64 v[34:35], v[80:81], 0, s[98:99]
	global_load_dword v10, v[34:35], off
	global_load_dword v11, v[34:35], off offset:256
	s_add_u32 s98, s98, s100
	s_cmp_le_u32 s33, 6
	s_cbranch_scc1 .Lini_ld_done
	v_lshl_add_u64 v[32:33], v[80:81], 0, s[98:99]
	global_load_dword v12, v[32:33], off
	global_load_dword v13, v[32:33], off offset:256
	s_add_u32 s98, s98, s100
	s_cmp_le_u32 s33, 7
	s_cbranch_scc1 .Lini_ld_done
	v_lshl_add_u64 v[34:35], v[80:81], 0, s[98:99]
	global_load_dword v14, v[34:35], off
	global_load_dword v15, v[34:35], off offset:256
	s_add_u32 s98, s98, s100
	s_cmp_le_u32 s33, 8
	s_cbranch_scc1 .Lini_ld_done
	v_lshl_add_u64 v[32:33], v[80:81], 0, s[98:99]
	global_load_dword v16, v[32:33], off
	global_load_dword v17, v[32:33], off offset:256
	s_add_u32 s98, s98, s100
	s_cmp_le_u32 s33, 9
	s_cbranch_scc1 .Lini_ld_done
	v_lshl_add_u64 v[34:35], v[80:81], 0, s[98:99]
	global_load_dword v18, v[34:35], off
	global_load_dword v19, v[34:35], off offset:256
	s_add_u32 s98, s98, s100
	s_cmp_le_u32 s33, 10
	s_cbranch_scc1 .Lini_ld_done
	v_lshl_add_u64 v[32:33], v[80:81], 0, s[98:99]
	global_load_dword v20, v[32:33], off
	global_load_dword v21, v[32:33], off offset:256
	s_add_u32 s98, s98, s100
	s_cmp_le_u32 s33, 11
	s_cbranch_scc1 .Lini_ld_done
	v_lshl_add_u64 v[34:35], v[80:81], 0, s[98:99]
	global_load_dword v22, v[34:35], off
	global_load_dword v23, v[34:35], off offset:256
	s_add_u32 s98, s98, s100
	s_cmp_le_u32 s33, 12
	s_cbranch_scc1 .Lini_ld_done
	v_lshl_add_u64 v[32:33], v[80:81], 0, s[98:99]
	global_load_dword v24, v[32:33], off
	global_load_dword v25, v[32:33], off offset:256
	s_add_u32 s98, s98, s100
	s_cmp_le_u32 s33, 13
	s_cbranch_scc1 .Lini_ld_done
	v_lshl_add_u64 v[34:35], v[80:81], 0, s[98:99]
	global_load_dword v26, v[34:35], off
	global_load_dword v27, v[34:35], off offset:256
	s_add_u32 s98, s98, s100
	s_cmp_le_u32 s33, 14
	s_cbranch_scc1 .Lini_ld_done
	v_lshl_add_u64 v[32:33], v[80:81], 0, s[98:99]
	global_load_dword v28, v[32:33], off
	global_load_dword v29, v[32:33], off offset:256
	s_add_u32 s98, s98, s100
	s_cmp_le_u32 s33, 15
	s_cbranch_scc1 .Lini_ld_done
	v_lshl_add_u64 v[34:35], v[80:81], 0, s[98:99]
	global_load_dword v30, v[34:35], off
	global_load_dword v31, v[34:35], off offset:256
	s_add_u32 s98, s98, s100
; __global__ void __launch_bounds__(NTHR, 2) fwd_megakernel(Args a) {
;     ...
;             for (int k = 0; k < kn; ++k) { const size_t t = (size_t)gw + (size_t)(k0 + k) * NGW;
;                 EL[k * 128 + lane] = EXPI[t * 128 + lane]; EL[k * 128 + 64 + lane] = EXPI[t * 128 + 64 + lane]; HW[k * 128 + lane] = 0.f; HW[k * 128 + 64 + lane] = 0.f; }
; #pragma unroll 1
;             for (int vs = 0; vs < 16; ++vs) {
;                 const unsigned char* Us = U8 + (size_t)vs * (16384 * 128) + sub * 16;
; #pragma unroll 1
;                 for (int k = 0; k < kn; ++k) {
;                     const size_t t = (size_t)gw + (size_t)(k0 + k) * NGW;
;                     u32x4 r[16];
; #pragma unroll
;                     for (int i = 0; i < 16; ++i) { const unsigned e = (unsigned)EL[k * 128 + 8 * i + grp]; r[i] = *(const u32x4*)(Us + e * 128u); }
;                     f32x2 f2[8];
;                     { const bf16_t* fr = F + t * D + vs * 128 + sub * 16; const u32x4 w0 = __builtin_nontemporal_load((const u32x4*)fr), w1 = __builtin_nontemporal_load((const u32x4*)(fr + 8));
; #pragma unroll
;                         for (int q = 0; q < 4; ++q) { f2[q] = (f32x2){bflo(w0[q]), bfhi(w0[q])}; f2[4 + q] = (f32x2){bflo(w1[q]), bfhi(w1[q])}; } }
.Lini_ld_done:
	v_mov_b32_e32 v36, v129
	s_waitcnt vmcnt(0)
	ds_write2st64_b32 v36, v0, v1 offset1:1
	ds_write2st64_b32 v36, v67, v67 offset0:32 offset1:33
	v_add_u32_e32 v36, 0x200, v36
	s_cmp_le_u32 s33, 1
	s_cbranch_scc1 .Lini_done
	ds_write2st64_b32 v36, v2, v3 offset1:1
	ds_write2st64_b32 v36, v67, v67 offset0:32 offset1:33
	v_add_u32_e32 v36, 0x200, v36
	s_cmp_le_u32 s33, 2
	s_cbranch_scc1 .Lini_done
	ds_write2st64_b32 v36, v4, v5 offset1:1
	ds_write2st64_b32 v36, v67, v67 offset0:32 offset1:33
	v_add_u32_e32 v36, 0x200, v36
	s_cmp_le_u32 s33, 3
	s_cbranch_scc1 .Lini_done
	ds_write2st64_b32 v36, v6, v7 offset1:1
	ds_write2st64_b32 v36, v67, v67 offset0:32 offset1:33
	v_add_u32_e32 v36, 0x200, v36
	s_cmp_le_u32 s33, 4
	s_cbranch_scc1 .Lini_done
	ds_write2st64_b32 v36, v8, v9 offset1:1
	ds_write2st64_b32 v36, v67, v67 offset0:32 offset1:33
	v_add_u32_e32 v36, 0x200, v36
	s_cmp_le_u32 s33, 5
	s_cbranch_scc1 .Lini_done
	ds_write2st64_b32 v36, v10, v11 offset1:1
	ds_write2st64_b32 v36, v67, v67 offset0:32 offset1:33
	v_add_u32_e32 v36, 0x200, v36
	s_cmp_le_u32 s33, 6
	s_cbranch_scc1 .Lini_done
	ds_write2st64_b32 v36, v12, v13 offset1:1
	ds_write2st64_b32 v36, v67, v67 offset0:32 offset1:33
	v_add_u32_e32 v36, 0x200, v36
	s_cmp_le_u32 s33, 7
	s_cbranch_scc1 .Lini_done
	ds_write2st64_b32 v36, v14, v15 offset1:1
	ds_write2st64_b32 v36, v67, v67 offset0:32 offset1:33
	v_add_u32_e32 v36, 0x200, v36
	s_cmp_le_u32 s33, 8
	s_cbranch_scc1 .Lini_done
	ds_write2st64_b32 v36, v16, v17 offset1:1
	ds_write2st64_b32 v36, v67, v67 offset0:32 offset1:33
	v_add_u32_e32 v36, 0x200, v36
	s_cmp_le_u32 s33, 9
	s_cbranch_scc1 .Lini_done
	ds_write2st64_b32 v36, v18, v19 offset1:1
	ds_write2st64_b32 v36, v67, v67 offset0:32 offset1:33
	v_add_u32_e32 v36, 0x200, v36
	s_cmp_le_u32 s33, 10
	s_cbranch_scc1 .Lini_done
	ds_write2st64_b32 v36, v20, v21 offset1:1
	ds_write2st64_b32 v36, v67, v67 offset0:32 offset1:33
	v_add_u32_e32 v36, 0x200, v36
	s_cmp_le_u32 s33, 11
	s_cbranch_scc1 .Lini_done
	ds_write2st64_b32 v36, v22, v23 offset1:1
	ds_write2st64_b32 v36, v67, v67 offset0:32 offset1:33
	v_add_u32_e32 v36, 0x200, v36
	s_cmp_le_u32 s33, 12
	s_cbranch_scc1 .Lini_done
	ds_write2st64_b32 v36, v24, v25 offset1:1
	ds_write2st64_b32 v36, v67, v67 offset0:32 offset1:33
	v_add_u32_e32 v36, 0x200, v36
	s_cmp_le_u32 s33, 13
	s_cbranch_scc1 .Lini_done
	ds_write2st64_b32 v36, v26, v27 offset1:1
	ds_write2st64_b32 v36, v67, v67 offset0:32 offset1:33
	v_add_u32_e32 v36, 0x200, v36
	s_cmp_le_u32 s33, 14
	s_cbranch_scc1 .Lini_done
	ds_write2st64_b32 v36, v28, v29 offset1:1
	ds_write2st64_b32 v36, v67, v67 offset0:32 offset1:33
	v_add_u32_e32 v36, 0x200, v36
	s_cmp_le_u32 s33, 15
	s_cbranch_scc1 .Lini_done
	ds_write2st64_b32 v36, v30, v31 offset1:1
	ds_write2st64_b32 v36, v67, v67 offset0:32 offset1:33
	v_add_u32_e32 v36, 0x200, v36
.Lini_done:
.LBB0_891:
	v_cndmask_b32_e64 v0, 0, 1, s[0:1]
	v_cmp_ne_u32_e64 s[28:29], 1, v0
	s_andn2_b64 vcc, exec, s[0:1]
	s_cbranch_vccnz .LBB0_896
	v_and_b32_e32 v184, 7, v64
	v_and_b32_e32 v208, 2, v64
	v_and_b32_e32 v209, 1, v64
	v_cmp_ne_u32_e64 s[12:13], 0, v208
	v_cmp_ne_u32_e64 s[14:15], 0, v209
	s_add_u32 s98, s50, 0x4000000
	s_addc_u32 s99, s51, 0
	v_lshlrev_b32_e32 v184, 4, v184
	s_lshl_b32 s100, s33, 4
	global_load_dwordx4 v[150:153], v[84:85], off offset:-16 nt
	global_load_dwordx4 v[154:157], v[84:85], off nt
	ds_read2_b32 v[158:159], v124 offset1:8
	ds_read2_b32 v[160:161], v124 offset0:16 offset1:24
	ds_read2_b32 v[162:163], v124 offset0:32 offset1:40
	ds_read2_b32 v[164:165], v124 offset0:48 offset1:56
	ds_read2_b32 v[166:167], v124 offset0:64 offset1:72
	ds_read2_b32 v[168:169], v124 offset0:80 offset1:88
	ds_read2_b32 v[170:171], v124 offset0:96 offset1:104
	ds_read2_b32 v[172:173], v124 offset0:112 offset1:120
	v_mov_b64_e32 v[92:93], v[84:85]
	v_mov_b64_e32 v[96:97], v[84:85]
	v_mov_b32_e32 v185, v124
	v_add_u32_e32 v187, v124, v82
	s_mov_b32 s101, 0
	s_waitcnt lgkmcnt(0)
	v_lshl_add_u32 v182, v158, 7, v184
	global_load_dwordx4 v[0:3], v182, s[98:99]
	v_lshl_add_u32 v183, v159, 7, v184
	global_load_dwordx4 v[4:7], v183, s[98:99]
	v_lshl_add_u32 v182, v160, 7, v184
	global_load_dwordx4 v[8:11], v182, s[98:99]
	v_lshl_add_u32 v183, v161, 7, v184
	global_load_dwordx4 v[12:15], v183, s[98:99]
	v_lshl_add_u32 v182, v162, 7, v184
	global_load_dwordx4 v[16:19], v182, s[98:99]
	v_lshl_add_u32 v183, v163, 7, v184
	global_load_dwordx4 v[20:23], v183, s[98:99]
	v_lshl_add_u32 v182, v164, 7, v184
	global_load_dwordx4 v[24:27], v182, s[98:99]
	v_lshl_add_u32 v183, v165, 7, v184
	global_load_dwordx4 v[28:31], v183, s[98:99]
	v_lshl_add_u32 v182, v166, 7, v184
	global_load_dwordx4 v[32:35], v182, s[98:99]
	v_lshl_add_u32 v183, v167, 7, v184
	global_load_dwordx4 v[36:39], v183, s[98:99]
	v_lshl_add_u32 v182, v168, 7, v184
	global_load_dwordx4 v[40:43], v182, s[98:99]
	v_lshl_add_u32 v183, v169, 7, v184
	global_load_dwordx4 v[44:47], v183, s[98:99]
	v_lshl_add_u32 v182, v170, 7, v184
	global_load_dwordx4 v[48:51], v182, s[98:99]
	v_lshl_add_u32 v183, v171, 7, v184
	global_load_dwordx4 v[52:55], v183, s[98:99]
	v_lshl_add_u32 v182, v172, 7, v184
	global_load_dwordx4 v[56:59], v182, s[98:99]
	v_lshl_add_u32 v183, v173, 7, v184
	global_load_dwordx4 v[60:63], v183, s[98:99]
	s_add_i32 s101, s101, 1
	s_cmp_lt_u32 s101, s33
	s_cbranch_scc1 .Lup_nw_p
	s_mov_b32 s101, 0
	s_add_u32 s98, s98, 0x200000
	s_addc_u32 s99, s99, 0
	v_lshl_add_u64 v[92:93], v[92:93], 0, s[78:79]
	v_mov_b32_e32 v185, v124
	v_mov_b64_e32 v[96:97], v[92:93]
	s_branch .Lup_jn_p

; __global__ void __launch_bounds__(NTHR, 2) fwd_megakernel(Args a) {
;     ...
;             for (int vs = 0; vs < 16; ++vs) {
;                 const unsigned char* Us = U8 + (size_t)vs * (16384 * 128) + sub * 16;
; #pragma unroll 1
;                 for (int k = 0; k < kn; ++k) {
;                     const size_t t = (size_t)gw + (size_t)(k0 + k) * NGW;
;                     u32x4 r[16];
; #pragma unroll
;                     for (int i = 0; i < 16; ++i) { const unsigned e = (unsigned)EL[k * 128 + 8 * i + grp]; r[i] = *(const u32x4*)(Us + e * 128u); }
;                     f32x2 f2[8];
;                     { const bf16_t* fr = F + t * D + vs * 128 + sub * 16; const u32x4 w0 = __builtin_nontemporal_load((const u32x4*)fr), w1 = __builtin_nontemporal_load((const u32x4*)(fr + 8));
; #pragma unroll
;                         for (int q = 0; q < 4; ++q) { f2[q] = (f32x2){bflo(w0[q]), bfhi(w0[q])}; f2[4 + q] = (f32x2){bflo(w1[q]), bfhi(w1[q])}; } }
;                     float accA = 0.f, accB = 0.f;
; #pragma unroll
;                     for (int i = 0; i < 16; ++i) {
;                         f32x2 a2 = {0.f, 0.f};
; #pragma unroll
;                         for (int q = 0; q < 4; ++q) { const int w = (int)r[i][q]; a2 += __builtin_amdgcn_cvt_pk_f32_fp8(w, false) * f2[2 * q]; a2 += __builtin_amdgcn_cvt_pk_f32_fp8(w, true) * f2[2 * q + 1]; }
;                         const float tot = red8(a2.x + a2.y);
;                         if (i < 8) accA = (sub == i) ? tot : accA; else accB = (sub == i - 8) ? tot : accB;
;                     }
;                     HW[k * 128 + sp] += accA; HW[k * 128 + 64 + sp] += accB;
.Lup_jn_p:
.Lup_loop:
	s_waitcnt vmcnt(16)
	ds_read2_b32 v[158:159], v185 offset1:8
	ds_read2_b32 v[160:161], v185 offset0:16 offset1:24
	ds_read2_b32 v[162:163], v185 offset0:32 offset1:40
	ds_read2_b32 v[164:165], v185 offset0:48 offset1:56
	ds_read2_b32 v[166:167], v185 offset0:64 offset1:72
	ds_read2_b32 v[168:169], v185 offset0:80 offset1:88
	ds_read2_b32 v[170:171], v185 offset0:96 offset1:104
	ds_read2_b32 v[172:173], v185 offset0:112 offset1:120
	ds_read2st64_b32 v[188:189], v187 offset0:32 offset1:33
	v_lshlrev_b32_e32 v98, 16, v150
	v_and_b32_e32 v99, 0xffff0000, v150
	v_lshlrev_b32_e32 v100, 16, v151
	v_and_b32_e32 v101, 0xffff0000, v151
	v_lshlrev_b32_e32 v102, 16, v152
	v_and_b32_e32 v103, 0xffff0000, v152
	v_lshlrev_b32_e32 v104, 16, v153
	v_and_b32_e32 v105, 0xffff0000, v153
	v_lshlrev_b32_e32 v106, 16, v154
	v_and_b32_e32 v107, 0xffff0000, v154
	v_lshlrev_b32_e32 v108, 16, v155
	v_and_b32_e32 v109, 0xffff0000, v155
	v_lshlrev_b32_e32 v110, 16, v156
	v_and_b32_e32 v111, 0xffff0000, v156
	v_lshlrev_b32_e32 v112, 16, v157
	v_and_b32_e32 v113, 0xffff0000, v157
	global_load_dwordx4 v[150:153], v[96:97], off offset:-16 nt
	global_load_dwordx4 v[154:157], v[96:97], off nt
	s_waitcnt vmcnt(17)
	v_cvt_pk_f32_fp8_e32 v[116:117], v0
	v_cvt_pk_f32_fp8_sdwa v[118:119], v0 src0_sel:WORD_1
	v_pk_fma_f32 v[174:175], v[116:117], v[98:99], 0 op_sel_hi:[1,1,0]
	v_cvt_pk_f32_fp8_e32 v[120:121], v1
	v_pk_fma_f32 v[174:175], v[118:119], v[100:101], v[174:175]
	v_cvt_pk_f32_fp8_sdwa v[122:123], v1 src0_sel:WORD_1
	v_pk_fma_f32 v[174:175], v[120:121], v[102:103], v[174:175]
	v_cvt_pk_f32_fp8_e32 v[116:117], v2
	v_pk_fma_f32 v[174:175], v[122:123], v[104:105], v[174:175]
	v_cvt_pk_f32_fp8_sdwa v[118:119], v2 src0_sel:WORD_1
	v_pk_fma_f32 v[174:175], v[116:117], v[106:107], v[174:175]
	v_cvt_pk_f32_fp8_e32 v[120:121], v3
	v_pk_fma_f32 v[174:175], v[118:119], v[108:109], v[174:175]
	v_cvt_pk_f32_fp8_sdwa v[122:123], v3 src0_sel:WORD_1
	s_waitcnt lgkmcnt(0)
	v_lshl_add_u32 v182, v158, 7, v184
	v_pk_fma_f32 v[174:175], v[120:121], v[110:111], v[174:175]
	global_load_dwordx4 v[0:3], v182, s[98:99]
	v_pk_fma_f32 v[174:175], v[122:123], v[112:113], v[174:175]
	s_waitcnt vmcnt(17)
	v_cvt_pk_f32_fp8_e32 v[116:117], v4
	v_cvt_pk_f32_fp8_sdwa v[118:119], v4 src0_sel:WORD_1
	v_add_f32_e32 v192, v174, v175
	v_pk_fma_f32 v[176:177], v[116:117], v[98:99], 0 op_sel_hi:[1,1,0]
	v_cvt_pk_f32_fp8_e32 v[120:121], v5
	v_pk_fma_f32 v[176:177], v[118:119], v[100:101], v[176:177]
	v_cvt_pk_f32_fp8_sdwa v[122:123], v5 src0_sel:WORD_1
	v_pk_fma_f32 v[176:177], v[120:121], v[102:103], v[176:177]
	v_cvt_pk_f32_fp8_e32 v[116:117], v6
	v_pk_fma_f32 v[176:177], v[122:123], v[104:105], v[176:177]
	v_cvt_pk_f32_fp8_sdwa v[118:119], v6 src0_sel:WORD_1
	v_pk_fma_f32 v[176:177], v[116:117], v[106:107], v[176:177]
	v_cvt_pk_f32_fp8_e32 v[120:121], v7
	v_pk_fma_f32 v[176:177], v[118:119], v[108:109], v[176:177]
	v_cvt_pk_f32_fp8_sdwa v[122:123], v7 src0_sel:WORD_1
	v_lshl_add_u32 v183, v159, 7, v184
	v_pk_fma_f32 v[176:177], v[120:121], v[110:111], v[176:177]
	global_load_dwordx4 v[4:7], v183, s[98:99]
	v_pk_fma_f32 v[176:177], v[122:123], v[112:113], v[176:177]
	s_waitcnt vmcnt(17)
	v_cvt_pk_f32_fp8_e32 v[116:117], v8
	v_cvt_pk_f32_fp8_sdwa v[118:119], v8 src0_sel:WORD_1
	v_add_f32_e32 v193, v176, v177
	v_pk_fma_f32 v[174:175], v[116:117], v[98:99], 0 op_sel_hi:[1,1,0]
	v_cvt_pk_f32_fp8_e32 v[120:121], v9
	v_pk_fma_f32 v[174:175], v[118:119], v[100:101], v[174:175]
	v_cvt_pk_f32_fp8_sdwa v[122:123], v9 src0_sel:WORD_1
	v_pk_fma_f32 v[174:175], v[120:121], v[102:103], v[174:175]
	v_cvt_pk_f32_fp8_e32 v[116:117], v10
	v_pk_fma_f32 v[174:175], v[122:123], v[104:105], v[174:175]
	v_cvt_pk_f32_fp8_sdwa v[118:119], v10 src0_sel:WORD_1
	v_pk_fma_f32 v[174:175], v[116:117], v[106:107], v[174:175]
	v_cvt_pk_f32_fp8_e32 v[120:121], v11
	v_pk_fma_f32 v[174:175], v[118:119], v[108:109], v[174:175]
	v_cvt_pk_f32_fp8_sdwa v[122:123], v11 src0_sel:WORD_1
	v_lshl_add_u32 v182, v160, 7, v184
	v_pk_fma_f32 v[174:175], v[120:121], v[110:111], v[174:175]
	global_load_dwordx4 v[8:11], v182, s[98:99]
	v_pk_fma_f32 v[174:175], v[122:123], v[112:113], v[174:175]
	s_waitcnt vmcnt(17)
	v_cvt_pk_f32_fp8_e32 v[116:117], v12
	v_cvt_pk_f32_fp8_sdwa v[118:119], v12 src0_sel:WORD_1
	v_add_f32_e32 v194, v174, v175
	v_pk_fma_f32 v[176:177], v[116:117], v[98:99], 0 op_sel_hi:[1,1,0]
	v_cvt_pk_f32_fp8_e32 v[120:121], v13
	v_pk_fma_f32 v[176:177], v[118:119], v[100:101], v[176:177]
	v_cvt_pk_f32_fp8_sdwa v[122:123], v13 src0_sel:WORD_1
	v_pk_fma_f32 v[176:177], v[120:121], v[102:103], v[176:177]
	v_cvt_pk_f32_fp8_e32 v[116:117], v14
	v_pk_fma_f32 v[176:177], v[122:123], v[104:105], v[176:177]
	v_cvt_pk_f32_fp8_sdwa v[118:119], v14 src0_sel:WORD_1
	v_pk_fma_f32 v[176:177], v[116:117], v[106:107], v[176:177]
	v_cvt_pk_f32_fp8_e32 v[120:121], v15
	v_pk_fma_f32 v[176:177], v[118:119], v[108:109], v[176:177]
	v_cvt_pk_f32_fp8_sdwa v[122:123], v15 src0_sel:WORD_1
	v_lshl_add_u32 v183, v161, 7, v184
	v_pk_fma_f32 v[176:177], v[120:121], v[110:111], v[176:177]
	global_load_dwordx4 v[12:15], v183, s[98:99]
	v_pk_fma_f32 v[176:177], v[122:123], v[112:113], v[176:177]
	s_waitcnt vmcnt(17)
; __global__ void __launch_bounds__(NTHR, 2) fwd_megakernel(Args a) {
;     ...
; #pragma unroll
;                     for (int i = 0; i < 16; ++i) {
;                         f32x2 a2 = {0.f, 0.f};
; #pragma unroll
;                         for (int q = 0; q < 4; ++q) { const int w = (int)r[i][q]; a2 += __builtin_amdgcn_cvt_pk_f32_fp8(w, false) * f2[2 * q]; a2 += __builtin_amdgcn_cvt_pk_f32_fp8(w, true) * f2[2 * q + 1]; }
;                         const float tot = red8(a2.x + a2.y);
;                         if (i < 8) accA = (sub == i) ? tot : accA; else accB = (sub == i - 8) ? tot : accB;
	v_cvt_pk_f32_fp8_e32 v[116:117], v16
	v_cvt_pk_f32_fp8_sdwa v[118:119], v16 src0_sel:WORD_1
	v_add_f32_e32 v195, v176, v177
	v_pk_fma_f32 v[174:175], v[116:117], v[98:99], 0 op_sel_hi:[1,1,0]
	v_cvt_pk_f32_fp8_e32 v[120:121], v17
	v_pk_fma_f32 v[174:175], v[118:119], v[100:101], v[174:175]
	v_cvt_pk_f32_fp8_sdwa v[122:123], v17 src0_sel:WORD_1
	v_pk_fma_f32 v[174:175], v[120:121], v[102:103], v[174:175]
	v_cvt_pk_f32_fp8_e32 v[116:117], v18
	v_pk_fma_f32 v[174:175], v[122:123], v[104:105], v[174:175]
	v_cvt_pk_f32_fp8_sdwa v[118:119], v18 src0_sel:WORD_1
	v_pk_fma_f32 v[174:175], v[116:117], v[106:107], v[174:175]
	v_cvt_pk_f32_fp8_e32 v[120:121], v19
	v_pk_fma_f32 v[174:175], v[118:119], v[108:109], v[174:175]
	v_cvt_pk_f32_fp8_sdwa v[122:123], v19 src0_sel:WORD_1
	v_lshl_add_u32 v182, v162, 7, v184
	v_pk_fma_f32 v[174:175], v[120:121], v[110:111], v[174:175]
	global_load_dwordx4 v[16:19], v182, s[98:99]
	v_pk_fma_f32 v[174:175], v[122:123], v[112:113], v[174:175]
	s_waitcnt vmcnt(17)
	v_cvt_pk_f32_fp8_e32 v[116:117], v20
	v_cvt_pk_f32_fp8_sdwa v[118:119], v20 src0_sel:WORD_1
	v_add_f32_e32 v196, v174, v175
	v_pk_fma_f32 v[176:177], v[116:117], v[98:99], 0 op_sel_hi:[1,1,0]
	v_cvt_pk_f32_fp8_e32 v[120:121], v21
	v_pk_fma_f32 v[176:177], v[118:119], v[100:101], v[176:177]
	v_cvt_pk_f32_fp8_sdwa v[122:123], v21 src0_sel:WORD_1
	v_pk_fma_f32 v[176:177], v[120:121], v[102:103], v[176:177]
	v_cvt_pk_f32_fp8_e32 v[116:117], v22
	v_pk_fma_f32 v[176:177], v[122:123], v[104:105], v[176:177]
	v_cvt_pk_f32_fp8_sdwa v[118:119], v22 src0_sel:WORD_1
	v_pk_fma_f32 v[176:177], v[116:117], v[106:107], v[176:177]
	v_cvt_pk_f32_fp8_e32 v[120:121], v23
	v_pk_fma_f32 v[176:177], v[118:119], v[108:109], v[176:177]
	v_cvt_pk_f32_fp8_sdwa v[122:123], v23 src0_sel:WORD_1
	v_lshl_add_u32 v183, v163, 7, v184
	v_pk_fma_f32 v[176:177], v[120:121], v[110:111], v[176:177]
	global_load_dwordx4 v[20:23], v183, s[98:99]
	v_pk_fma_f32 v[176:177], v[122:123], v[112:113], v[176:177]
	s_waitcnt vmcnt(17)
	v_cvt_pk_f32_fp8_e32 v[116:117], v24
	v_cvt_pk_f32_fp8_sdwa v[118:119], v24 src0_sel:WORD_1
	v_add_f32_e32 v197, v176, v177
	v_pk_fma_f32 v[174:175], v[116:117], v[98:99], 0 op_sel_hi:[1,1,0]
	v_cvt_pk_f32_fp8_e32 v[120:121], v25
	v_pk_fma_f32 v[174:175], v[118:119], v[100:101], v[174:175]
	v_cvt_pk_f32_fp8_sdwa v[122:123], v25 src0_sel:WORD_1
	v_pk_fma_f32 v[174:175], v[120:121], v[102:103], v[174:175]
	v_cvt_pk_f32_fp8_e32 v[116:117], v26
	v_pk_fma_f32 v[174:175], v[122:123], v[104:105], v[174:175]
	v_cvt_pk_f32_fp8_sdwa v[118:119], v26 src0_sel:WORD_1
	v_pk_fma_f32 v[174:175], v[116:117], v[106:107], v[174:175]
	v_cvt_pk_f32_fp8_e32 v[120:121], v27
	v_pk_fma_f32 v[174:175], v[118:119], v[108:109], v[174:175]
	v_cvt_pk_f32_fp8_sdwa v[122:123], v27 src0_sel:WORD_1
	v_lshl_add_u32 v182, v164, 7, v184
	v_pk_fma_f32 v[174:175], v[120:121], v[110:111], v[174:175]
	global_load_dwordx4 v[24:27], v182, s[98:99]
	v_pk_fma_f32 v[174:175], v[122:123], v[112:113], v[174:175]
	s_waitcnt vmcnt(17)
	v_cvt_pk_f32_fp8_e32 v[116:117], v28
	v_cvt_pk_f32_fp8_sdwa v[118:119], v28 src0_sel:WORD_1
	v_add_f32_e32 v198, v174, v175
	v_pk_fma_f32 v[176:177], v[116:117], v[98:99], 0 op_sel_hi:[1,1,0]
	v_cvt_pk_f32_fp8_e32 v[120:121], v29
	v_pk_fma_f32 v[176:177], v[118:119], v[100:101], v[176:177]
	v_cvt_pk_f32_fp8_sdwa v[122:123], v29 src0_sel:WORD_1
	v_pk_fma_f32 v[176:177], v[120:121], v[102:103], v[176:177]
	v_cvt_pk_f32_fp8_e32 v[116:117], v30
	v_pk_fma_f32 v[176:177], v[122:123], v[104:105], v[176:177]
	v_cvt_pk_f32_fp8_sdwa v[118:119], v30 src0_sel:WORD_1
	v_pk_fma_f32 v[176:177], v[116:117], v[106:107], v[176:177]
	v_cvt_pk_f32_fp8_e32 v[120:121], v31
	v_pk_fma_f32 v[176:177], v[118:119], v[108:109], v[176:177]
	v_cvt_pk_f32_fp8_sdwa v[122:123], v31 src0_sel:WORD_1
	v_lshl_add_u32 v183, v165, 7, v184
	v_pk_fma_f32 v[176:177], v[120:121], v[110:111], v[176:177]
	global_load_dwordx4 v[28:31], v183, s[98:99]
	v_pk_fma_f32 v[176:177], v[122:123], v[112:113], v[176:177]
	s_waitcnt vmcnt(17)
	v_cvt_pk_f32_fp8_e32 v[116:117], v32
	v_cvt_pk_f32_fp8_sdwa v[118:119], v32 src0_sel:WORD_1
	v_add_f32_e32 v199, v176, v177
	v_pk_fma_f32 v[174:175], v[116:117], v[98:99], 0 op_sel_hi:[1,1,0]
	v_cvt_pk_f32_fp8_e32 v[120:121], v33
	v_pk_fma_f32 v[174:175], v[118:119], v[100:101], v[174:175]
	v_add_f32_dpp v192, v192, v192 row_shl:4 row_mask:0xf bank_mask:0x5
	v_cvt_pk_f32_fp8_sdwa v[122:123], v33 src0_sel:WORD_1
	v_pk_fma_f32 v[174:175], v[120:121], v[102:103], v[174:175]
	v_cvt_pk_f32_fp8_e32 v[116:117], v34
	v_pk_fma_f32 v[174:175], v[122:123], v[104:105], v[174:175]
	v_add_f32_dpp v192, v196, v196 row_shr:4 row_mask:0xf bank_mask:0xa
	v_cvt_pk_f32_fp8_sdwa v[118:119], v34 src0_sel:WORD_1
	v_pk_fma_f32 v[174:175], v[116:117], v[106:107], v[174:175]
	v_cvt_pk_f32_fp8_e32 v[120:121], v35
	v_pk_fma_f32 v[174:175], v[118:119], v[108:109], v[174:175]
	v_add_f32_dpp v193, v193, v193 row_shl:4 row_mask:0xf bank_mask:0x5
	v_cvt_pk_f32_fp8_sdwa v[122:123], v35 src0_sel:WORD_1
	v_lshl_add_u32 v182, v166, 7, v184
	v_pk_fma_f32 v[174:175], v[120:121], v[110:111], v[174:175]
	global_load_dwordx4 v[32:35], v182, s[98:99]
	v_add_f32_dpp v193, v197, v197 row_shr:4 row_mask:0xf bank_mask:0xa
	v_pk_fma_f32 v[174:175], v[122:123], v[112:113], v[174:175]
	s_waitcnt vmcnt(17)
; __global__ void __launch_bounds__(NTHR, 2) fwd_megakernel(Args a) {
;     ...
; #pragma unroll
;                     for (int i = 0; i < 16; ++i) {
;                         f32x2 a2 = {0.f, 0.f};
; #pragma unroll
;                         for (int q = 0; q < 4; ++q) { const int w = (int)r[i][q]; a2 += __builtin_amdgcn_cvt_pk_f32_fp8(w, false) * f2[2 * q]; a2 += __builtin_amdgcn_cvt_pk_f32_fp8(w, true) * f2[2 * q + 1]; }
;                         const float tot = red8(a2.x + a2.y);
;                         if (i < 8) accA = (sub == i) ? tot : accA; else accB = (sub == i - 8) ? tot : accB;
;                     }
;                     HW[k * 128 + sp] += accA; HW[k * 128 + 64 + sp] += accB;
	v_cvt_pk_f32_fp8_e32 v[116:117], v36
	v_cvt_pk_f32_fp8_sdwa v[118:119], v36 src0_sel:WORD_1
	v_add_f32_e32 v200, v174, v175
	v_pk_fma_f32 v[176:177], v[116:117], v[98:99], 0 op_sel_hi:[1,1,0]
	v_cvt_pk_f32_fp8_e32 v[120:121], v37
	v_pk_fma_f32 v[176:177], v[118:119], v[100:101], v[176:177]
	v_add_f32_dpp v194, v194, v194 row_shl:4 row_mask:0xf bank_mask:0x5
	v_cvt_pk_f32_fp8_sdwa v[122:123], v37 src0_sel:WORD_1
	v_pk_fma_f32 v[176:177], v[120:121], v[102:103], v[176:177]
	v_cvt_pk_f32_fp8_e32 v[116:117], v38
	v_pk_fma_f32 v[176:177], v[122:123], v[104:105], v[176:177]
	v_add_f32_dpp v194, v198, v198 row_shr:4 row_mask:0xf bank_mask:0xa
	v_cvt_pk_f32_fp8_sdwa v[118:119], v38 src0_sel:WORD_1
	v_pk_fma_f32 v[176:177], v[116:117], v[106:107], v[176:177]
	v_cvt_pk_f32_fp8_e32 v[120:121], v39
	v_pk_fma_f32 v[176:177], v[118:119], v[108:109], v[176:177]
	v_add_f32_dpp v195, v195, v195 row_shl:4 row_mask:0xf bank_mask:0x5
	v_cvt_pk_f32_fp8_sdwa v[122:123], v39 src0_sel:WORD_1
	v_lshl_add_u32 v183, v167, 7, v184
	v_pk_fma_f32 v[176:177], v[120:121], v[110:111], v[176:177]
	global_load_dwordx4 v[36:39], v183, s[98:99]
	v_add_f32_dpp v195, v199, v199 row_shr:4 row_mask:0xf bank_mask:0xa
	v_pk_fma_f32 v[176:177], v[122:123], v[112:113], v[176:177]
	s_waitcnt vmcnt(17)
	v_cvt_pk_f32_fp8_e32 v[116:117], v40
	v_cvt_pk_f32_fp8_sdwa v[118:119], v40 src0_sel:WORD_1
	v_add_f32_e32 v201, v176, v177
	v_pk_fma_f32 v[174:175], v[116:117], v[98:99], 0 op_sel_hi:[1,1,0]
	v_cvt_pk_f32_fp8_e32 v[120:121], v41
	v_pk_fma_f32 v[174:175], v[118:119], v[100:101], v[174:175]
	v_cndmask_b32_e64 v208, v192, v194, s[12:13]
	v_cvt_pk_f32_fp8_sdwa v[122:123], v41 src0_sel:WORD_1
	v_pk_fma_f32 v[174:175], v[120:121], v[102:103], v[174:175]
	v_cvt_pk_f32_fp8_e32 v[116:117], v42
	v_pk_fma_f32 v[174:175], v[122:123], v[104:105], v[174:175]
	v_cndmask_b32_e64 v209, v194, v192, s[12:13]
	v_cvt_pk_f32_fp8_sdwa v[118:119], v42 src0_sel:WORD_1
	v_pk_fma_f32 v[174:175], v[116:117], v[106:107], v[174:175]
	v_cvt_pk_f32_fp8_e32 v[120:121], v43
	v_pk_fma_f32 v[174:175], v[118:119], v[108:109], v[174:175]
	v_cndmask_b32_e64 v211, v195, v193, s[12:13]
	v_cvt_pk_f32_fp8_sdwa v[122:123], v43 src0_sel:WORD_1
	v_lshl_add_u32 v182, v168, 7, v184
	v_pk_fma_f32 v[174:175], v[120:121], v[110:111], v[174:175]
	global_load_dwordx4 v[40:43], v182, s[98:99]
	v_cndmask_b32_e64 v210, v193, v195, s[12:13]
	v_pk_fma_f32 v[174:175], v[122:123], v[112:113], v[174:175]
	s_waitcnt vmcnt(17)
	v_cvt_pk_f32_fp8_e32 v[116:117], v44
	v_cvt_pk_f32_fp8_sdwa v[118:119], v44 src0_sel:WORD_1
	v_add_f32_e32 v202, v174, v175
	v_pk_fma_f32 v[176:177], v[116:117], v[98:99], 0 op_sel_hi:[1,1,0]
	v_cvt_pk_f32_fp8_e32 v[120:121], v45
	v_pk_fma_f32 v[176:177], v[118:119], v[100:101], v[176:177]
	v_add_f32_dpp v208, v209, v208 quad_perm:[2,3,0,1] row_mask:0xf bank_mask:0xf
	v_cvt_pk_f32_fp8_sdwa v[122:123], v45 src0_sel:WORD_1
	v_pk_fma_f32 v[176:177], v[120:121], v[102:103], v[176:177]
	v_cvt_pk_f32_fp8_e32 v[116:117], v46
	v_pk_fma_f32 v[176:177], v[122:123], v[104:105], v[176:177]
	v_add_f32_dpp v210, v211, v210 quad_perm:[2,3,0,1] row_mask:0xf bank_mask:0xf
	v_cvt_pk_f32_fp8_sdwa v[118:119], v46 src0_sel:WORD_1
	v_pk_fma_f32 v[176:177], v[116:117], v[106:107], v[176:177]
	v_cvt_pk_f32_fp8_e32 v[120:121], v47
	v_pk_fma_f32 v[176:177], v[118:119], v[108:109], v[176:177]
	v_cndmask_b32_e64 v209, v210, v208, s[14:15]
	v_cvt_pk_f32_fp8_sdwa v[122:123], v47 src0_sel:WORD_1
	v_lshl_add_u32 v183, v169, 7, v184
	v_pk_fma_f32 v[176:177], v[120:121], v[110:111], v[176:177]
	global_load_dwordx4 v[44:47], v183, s[98:99]
	v_cndmask_b32_e64 v211, v208, v210, s[14:15]
	v_pk_fma_f32 v[176:177], v[122:123], v[112:113], v[176:177]
	s_waitcnt vmcnt(17)
	v_cvt_pk_f32_fp8_e32 v[116:117], v48
	v_cvt_pk_f32_fp8_sdwa v[118:119], v48 src0_sel:WORD_1
	v_add_f32_e32 v203, v176, v177
	v_pk_fma_f32 v[174:175], v[116:117], v[98:99], 0 op_sel_hi:[1,1,0]
	v_cvt_pk_f32_fp8_e32 v[120:121], v49
	v_pk_fma_f32 v[174:175], v[118:119], v[100:101], v[174:175]
	v_add_f32_dpp v180, v209, v211 quad_perm:[1,0,3,2] row_mask:0xf bank_mask:0xf
	v_cvt_pk_f32_fp8_sdwa v[122:123], v49 src0_sel:WORD_1
	v_pk_fma_f32 v[174:175], v[120:121], v[102:103], v[174:175]
	v_cvt_pk_f32_fp8_e32 v[116:117], v50
	v_pk_fma_f32 v[174:175], v[122:123], v[104:105], v[174:175]
	v_cvt_pk_f32_fp8_sdwa v[118:119], v50 src0_sel:WORD_1
	v_pk_fma_f32 v[174:175], v[116:117], v[106:107], v[174:175]
	v_cvt_pk_f32_fp8_e32 v[120:121], v51
	v_pk_fma_f32 v[174:175], v[118:119], v[108:109], v[174:175]
	v_cvt_pk_f32_fp8_sdwa v[122:123], v51 src0_sel:WORD_1
	v_lshl_add_u32 v182, v170, 7, v184
	v_pk_fma_f32 v[174:175], v[120:121], v[110:111], v[174:175]
	global_load_dwordx4 v[48:51], v182, s[98:99]
	v_pk_fma_f32 v[174:175], v[122:123], v[112:113], v[174:175]
	s_waitcnt vmcnt(17)
; __global__ void __launch_bounds__(NTHR, 2) fwd_megakernel(Args a) {
;     ...
; #pragma unroll
;                     for (int i = 0; i < 16; ++i) {
;                         f32x2 a2 = {0.f, 0.f};
; #pragma unroll
;                         for (int q = 0; q < 4; ++q) { const int w = (int)r[i][q]; a2 += __builtin_amdgcn_cvt_pk_f32_fp8(w, false) * f2[2 * q]; a2 += __builtin_amdgcn_cvt_pk_f32_fp8(w, true) * f2[2 * q + 1]; }
;                         const float tot = red8(a2.x + a2.y);
;                         if (i < 8) accA = (sub == i) ? tot : accA; else accB = (sub == i - 8) ? tot : accB;
;                     }
;                     HW[k * 128 + sp] += accA; HW[k * 128 + 64 + sp] += accB;
	v_cvt_pk_f32_fp8_e32 v[116:117], v52
	v_cvt_pk_f32_fp8_sdwa v[118:119], v52 src0_sel:WORD_1
	v_add_f32_e32 v204, v174, v175
	v_pk_fma_f32 v[176:177], v[116:117], v[98:99], 0 op_sel_hi:[1,1,0]
	v_cvt_pk_f32_fp8_e32 v[120:121], v53
	v_pk_fma_f32 v[176:177], v[118:119], v[100:101], v[176:177]
	v_cvt_pk_f32_fp8_sdwa v[122:123], v53 src0_sel:WORD_1
	v_pk_fma_f32 v[176:177], v[120:121], v[102:103], v[176:177]
	v_cvt_pk_f32_fp8_e32 v[116:117], v54
	v_pk_fma_f32 v[176:177], v[122:123], v[104:105], v[176:177]
	v_cvt_pk_f32_fp8_sdwa v[118:119], v54 src0_sel:WORD_1
	v_pk_fma_f32 v[176:177], v[116:117], v[106:107], v[176:177]
	v_cvt_pk_f32_fp8_e32 v[120:121], v55
	v_pk_fma_f32 v[176:177], v[118:119], v[108:109], v[176:177]
	v_cvt_pk_f32_fp8_sdwa v[122:123], v55 src0_sel:WORD_1
	v_lshl_add_u32 v183, v171, 7, v184
	v_pk_fma_f32 v[176:177], v[120:121], v[110:111], v[176:177]
	global_load_dwordx4 v[52:55], v183, s[98:99]
	v_pk_fma_f32 v[176:177], v[122:123], v[112:113], v[176:177]
	s_waitcnt vmcnt(17)
	v_cvt_pk_f32_fp8_e32 v[116:117], v56
	v_cvt_pk_f32_fp8_sdwa v[118:119], v56 src0_sel:WORD_1
	v_add_f32_e32 v205, v176, v177
	v_pk_fma_f32 v[174:175], v[116:117], v[98:99], 0 op_sel_hi:[1,1,0]
	v_cvt_pk_f32_fp8_e32 v[120:121], v57
	v_pk_fma_f32 v[174:175], v[118:119], v[100:101], v[174:175]
	v_cvt_pk_f32_fp8_sdwa v[122:123], v57 src0_sel:WORD_1
	v_pk_fma_f32 v[174:175], v[120:121], v[102:103], v[174:175]
	v_cvt_pk_f32_fp8_e32 v[116:117], v58
	v_pk_fma_f32 v[174:175], v[122:123], v[104:105], v[174:175]
	v_cvt_pk_f32_fp8_sdwa v[118:119], v58 src0_sel:WORD_1
	v_pk_fma_f32 v[174:175], v[116:117], v[106:107], v[174:175]
	v_cvt_pk_f32_fp8_e32 v[120:121], v59
	v_pk_fma_f32 v[174:175], v[118:119], v[108:109], v[174:175]
	v_cvt_pk_f32_fp8_sdwa v[122:123], v59 src0_sel:WORD_1
	v_lshl_add_u32 v182, v172, 7, v184
	v_pk_fma_f32 v[174:175], v[120:121], v[110:111], v[174:175]
	global_load_dwordx4 v[56:59], v182, s[98:99]
	v_pk_fma_f32 v[174:175], v[122:123], v[112:113], v[174:175]
	s_waitcnt vmcnt(17)
	v_cvt_pk_f32_fp8_e32 v[116:117], v60
	v_cvt_pk_f32_fp8_sdwa v[118:119], v60 src0_sel:WORD_1
	v_add_f32_e32 v206, v174, v175
	v_pk_fma_f32 v[176:177], v[116:117], v[98:99], 0 op_sel_hi:[1,1,0]
	v_cvt_pk_f32_fp8_e32 v[120:121], v61
	v_pk_fma_f32 v[176:177], v[118:119], v[100:101], v[176:177]
	v_cvt_pk_f32_fp8_sdwa v[122:123], v61 src0_sel:WORD_1
	v_pk_fma_f32 v[176:177], v[120:121], v[102:103], v[176:177]
	v_cvt_pk_f32_fp8_e32 v[116:117], v62
	v_pk_fma_f32 v[176:177], v[122:123], v[104:105], v[176:177]
	v_cvt_pk_f32_fp8_sdwa v[118:119], v62 src0_sel:WORD_1
	v_pk_fma_f32 v[176:177], v[116:117], v[106:107], v[176:177]
	v_cvt_pk_f32_fp8_e32 v[120:121], v63
	v_pk_fma_f32 v[176:177], v[118:119], v[108:109], v[176:177]
	v_cvt_pk_f32_fp8_sdwa v[122:123], v63 src0_sel:WORD_1
	v_lshl_add_u32 v183, v173, 7, v184
	v_pk_fma_f32 v[176:177], v[120:121], v[110:111], v[176:177]
	global_load_dwordx4 v[60:63], v183, s[98:99]
	v_pk_fma_f32 v[176:177], v[122:123], v[112:113], v[176:177]
	s_add_i32 s100, s100, -1
	v_add_f32_e32 v207, v176, v177
	v_add_f32_dpp v200, v200, v200 row_shl:4 row_mask:0xf bank_mask:0x5
	v_add_f32_dpp v200, v204, v204 row_shr:4 row_mask:0xf bank_mask:0xa
	v_add_f32_dpp v201, v201, v201 row_shl:4 row_mask:0xf bank_mask:0x5
	v_add_f32_dpp v201, v205, v205 row_shr:4 row_mask:0xf bank_mask:0xa
	v_add_f32_dpp v202, v202, v202 row_shl:4 row_mask:0xf bank_mask:0x5
	v_add_f32_dpp v202, v206, v206 row_shr:4 row_mask:0xf bank_mask:0xa
	v_add_f32_dpp v203, v203, v203 row_shl:4 row_mask:0xf bank_mask:0x5
	v_add_f32_dpp v203, v207, v207 row_shr:4 row_mask:0xf bank_mask:0xa
	v_cndmask_b32_e64 v208, v200, v202, s[12:13]
	v_cndmask_b32_e64 v209, v202, v200, s[12:13]
	v_cndmask_b32_e64 v211, v203, v201, s[12:13]
	v_cndmask_b32_e64 v210, v201, v203, s[12:13]
	v_add_f32_dpp v208, v209, v208 quad_perm:[2,3,0,1] row_mask:0xf bank_mask:0xf
	v_add_f32_dpp v210, v211, v210 quad_perm:[2,3,0,1] row_mask:0xf bank_mask:0xf
	v_cndmask_b32_e64 v209, v210, v208, s[14:15]
	v_cndmask_b32_e64 v211, v208, v210, s[14:15]
	v_add_f32_e32 v188, v180, v188
	v_add_f32_dpp v181, v209, v211 quad_perm:[1,0,3,2] row_mask:0xf bank_mask:0xf
	s_nop 0
	v_add_f32_e32 v189, v181, v189
	ds_write2st64_b32 v187, v188, v189 offset0:32 offset1:33
	v_add_u32_e32 v187, v185, v82
	s_add_i32 s101, s101, 1
	s_cmp_lt_u32 s101, s33
	s_cbranch_scc1 .Lup_nw_l
	s_mov_b32 s101, 0
	s_add_u32 s98, s98, 0x200000
	s_addc_u32 s99, s99, 0
	v_lshl_add_u64 v[92:93], v[92:93], 0, s[78:79]
	v_mov_b32_e32 v185, v124
	v_mov_b64_e32 v[96:97], v[92:93]
	s_branch .Lup_jn_l
